# adds: grid-barrier census loads issued together
# baseline (speedup 1.0000x reference)
.LBB0_720:
	s_waitcnt lgkmcnt(0)
	v_readlane_b32 s4, v238, 41
	v_readlane_b32 s5, v238, 42
	v_readlane_b32 s6, v236, 29
	s_nop 4
	global_load_dword v0, v1, s[4:5] sc1
	global_load_dword v2, v1, s[4:5] offset:256 sc1
	global_load_dword v3, v1, s[4:5] offset:512 sc1
	global_load_dword v4, v1, s[4:5] offset:768 sc1
	global_load_dword v5, v1, s[4:5] offset:1024 sc1
	global_load_dword v6, v1, s[4:5] offset:1280 sc1
	global_load_dword v7, v1, s[4:5] offset:1536 sc1
	global_load_dword v8, v1, s[4:5] offset:1792 sc1
	global_load_dword v9, v1, s[4:5] offset:2048 sc1
	global_load_dword v10, v1, s[4:5] offset:2304 sc1
	global_load_dword v11, v1, s[4:5] offset:2560 sc1
	global_load_dword v12, v1, s[4:5] offset:2816 sc1
	global_load_dword v13, v1, s[4:5] offset:3072 sc1
	global_load_dword v14, v1, s[4:5] offset:3328 sc1
	global_load_dword v15, v1, s[4:5] offset:3584 sc1
	global_load_dword v16, v1, s[4:5] offset:3840 sc1
	s_waitcnt vmcnt(0)
	v_add_u32_e32 v17, v2, v0
	v_add_u32_e32 v17, v17, v3
	v_add_u32_e32 v17, v17, v4
	v_add_u32_e32 v17, v17, v5
	v_add_u32_e32 v17, v17, v6
	v_add_u32_e32 v17, v17, v7
	v_add_u32_e32 v17, v17, v8
	v_add_u32_e32 v17, v17, v9
	v_add_u32_e32 v17, v17, v10
	v_add_u32_e32 v17, v17, v11
	v_add_u32_e32 v17, v17, v12
	v_add_u32_e32 v17, v17, v13
	v_add_u32_e32 v17, v17, v14
	v_add_u32_e32 v17, v17, v15
	v_add_u32_e32 v17, v17, v16
	s_mov_b64 s[4:5], -1
	v_cmp_eq_u32_e32 vcc, s6, v17
	s_mov_b64 s[6:7], -1
	s_cbranch_vccnz .LBB0_719
	s_and_b32 s4, s2, 0xff
	s_cmp_eq_u32 s4, 0
	s_mov_b64 s[4:5], -1
	s_mov_b64 s[8:9], -1
	s_sleep 1
	s_cbranch_scc0 .LBB0_724
	v_readlane_b32 s4, v238, 39
	v_readlane_b32 s5, v238, 40
	s_nop 4
	global_load_dword v17, v1, s[4:5] sc1
	s_waitcnt vmcnt(0)
	v_cmp_eq_u32_e32 vcc, 0, v17
	s_cbranch_vccnz .LBB0_726
	s_mov_b64 s[8:9], 0
	s_mov_b64 s[4:5], -1
